# MLA epilogue sub-block A: permlane32_swap pairs the half-wave 8-byte pieces into 16-byte stores (on top of v096)
# baseline (speedup 1.0000x reference)
.LBB0_216:
	ds_bpermute_b32 v64, v218, v203
	s_lshl_b64 s[2:3], s[6:7], 23
	s_add_u32 s0, s80, s2
	s_addc_u32 s4, s81, s3
	v_lshlrev_b32_e32 v188, 3, v215
	s_waitcnt lgkmcnt(0)
	v_add_f32_e32 v64, v203, v64
	v_div_scale_f32 v65, s[2:3], v64, v64, 1.0
	v_rcp_f32_e32 v66, v65
	s_lshl_b32 s2, s8, 7
	s_add_u32 s2, s0, s2
	s_addc_u32 s3, s4, 0
	v_fma_f32 v67, -v65, v66, 1.0
	v_fmac_f32_e32 v66, v67, v66
	v_div_scale_f32 v67, vcc, 1.0, v64, 1.0
	v_mul_f32_e32 v68, v67, v66
	v_fma_f32 v69, -v65, v68, v67
	v_fmac_f32_e32 v68, v69, v66
	v_fma_f32 v65, -v65, v68, v67
	v_div_fmas_f32 v65, v65, v66, v68
	v_div_fixup_f32 v64, v65, v64, 1.0
	v_lshlrev_b64 v[66:67], 10, v[192:193]
	v_lshl_add_u64 v[66:67], s[2:3], 0, v[66:67]
	v_pk_mul_f32 v[32:33], v[32:33], v[64:65] op_sel_hi:[1,0]
	v_pk_mul_f32 v[34:35], v[34:35], v[64:65] op_sel_hi:[1,0]
	v_lshl_add_u64 v[66:67], v[66:67], 0, v[188:189]
	v_cvt_pk_bf16_f32 v32, v32, v33
	v_cvt_pk_bf16_f32 v33, v34, v35
	v_and_b32_e32 v248, 32, v204
	v_lshrrev_b32_e32 v248, 2, v248
	v_mov_b32_e32 v249, v189
	v_mov_b64_e32 v[240:241], v[32:33]
	v_pk_mul_f32 v[32:33], v[36:37], v[64:65] op_sel_hi:[1,0]
	v_pk_mul_f32 v[34:35], v[38:39], v[64:65] op_sel_hi:[1,0]
	v_cvt_pk_bf16_f32 v32, v32, v33
	v_cvt_pk_bf16_f32 v33, v34, v35
	v_mov_b64_e32 v[242:243], v[32:33]
	s_nop 1
	v_permlane32_swap_b32 v240, v242
	v_permlane32_swap_b32 v241, v243
	v_lshl_add_u64 v[250:251], v[66:67], 0, v[248:249]
	global_store_dwordx4 v[250:251], v[240:243], off
	s_nop 1
	v_pk_mul_f32 v[32:33], v[40:41], v[64:65] op_sel_hi:[1,0]
	v_pk_mul_f32 v[34:35], v[42:43], v[64:65] op_sel_hi:[1,0]
	v_cvt_pk_bf16_f32 v32, v32, v33
	v_cvt_pk_bf16_f32 v33, v34, v35
	ds_bpermute_b32 v36, v218, v201
	v_mov_b64_e32 v[244:245], v[32:33]
	v_pk_mul_f32 v[32:33], v[44:45], v[64:65] op_sel_hi:[1,0]
	v_pk_mul_f32 v[34:35], v[46:47], v[64:65] op_sel_hi:[1,0]
	v_cvt_pk_bf16_f32 v32, v32, v33
	v_cvt_pk_bf16_f32 v33, v34, v35
	v_mov_b64_e32 v[246:247], v[32:33]
	s_nop 1
	v_permlane32_swap_b32 v244, v246
	v_permlane32_swap_b32 v245, v247
	v_lshl_add_u64 v[250:251], v[66:67], 0, v[248:249]
	global_store_dwordx4 v[250:251], v[244:247], off offset:32
	s_nop 1
	v_pk_mul_f32 v[32:33], v[48:49], v[64:65] op_sel_hi:[1,0]
	v_pk_mul_f32 v[34:35], v[50:51], v[64:65] op_sel_hi:[1,0]
	v_cvt_pk_bf16_f32 v32, v32, v33
	v_cvt_pk_bf16_f32 v33, v34, v35
	v_mov_b64_e32 v[240:241], v[32:33]
	v_pk_mul_f32 v[32:33], v[52:53], v[64:65] op_sel_hi:[1,0]
	v_pk_mul_f32 v[34:35], v[54:55], v[64:65] op_sel_hi:[1,0]
	s_waitcnt lgkmcnt(0)
	v_add_f32_e32 v36, v201, v36
	v_cvt_pk_bf16_f32 v32, v32, v33
	v_cvt_pk_bf16_f32 v33, v34, v35
	v_div_scale_f32 v37, s[4:5], v36, v36, 1.0
	v_mov_b64_e32 v[242:243], v[32:33]
	s_nop 1
	v_permlane32_swap_b32 v240, v242
	v_permlane32_swap_b32 v241, v243
	v_lshl_add_u64 v[250:251], v[66:67], 0, v[248:249]
	global_store_dwordx4 v[250:251], v[240:243], off offset:64
	s_nop 1
	v_pk_mul_f32 v[32:33], v[56:57], v[64:65] op_sel_hi:[1,0]
	v_pk_mul_f32 v[34:35], v[58:59], v[64:65] op_sel_hi:[1,0]
	v_rcp_f32_e32 v38, v37
	v_cvt_pk_bf16_f32 v32, v32, v33
	v_cvt_pk_bf16_f32 v33, v34, v35
	v_mov_b64_e32 v[244:245], v[32:33]
	v_pk_mul_f32 v[32:33], v[60:61], v[64:65] op_sel_hi:[1,0]
	v_pk_mul_f32 v[34:35], v[62:63], v[64:65] op_sel_hi:[1,0]
	v_cvt_pk_bf16_f32 v32, v32, v33
	v_cvt_pk_bf16_f32 v33, v34, v35
	v_mov_b64_e32 v[246:247], v[32:33]
	s_nop 1
	v_permlane32_swap_b32 v244, v246
	v_permlane32_swap_b32 v245, v247
	v_lshl_add_u64 v[250:251], v[66:67], 0, v[248:249]
	global_store_dwordx4 v[250:251], v[244:247], off offset:96
	s_nop 1
	v_fma_f32 v32, -v37, v38, 1.0
	v_fmac_f32_e32 v38, v32, v38
	v_div_scale_f32 v32, vcc, 1.0, v36, 1.0
	v_mul_f32_e32 v33, v32, v38
	v_fma_f32 v34, -v37, v33, v32
	v_fmac_f32_e32 v33, v34, v38
	v_fma_f32 v32, -v37, v33, v32
	v_div_fmas_f32 v32, v32, v38, v33
	v_div_fixup_f32 v34, v32, v36, 1.0
	v_lshlrev_b64 v[32:33], 10, v[190:191]
	v_lshl_add_u64 v[32:33], s[2:3], 0, v[32:33]
	v_pk_mul_f32 v[0:1], v[0:1], v[34:35] op_sel_hi:[1,0]
	v_lshl_add_u64 v[32:33], v[32:33], 0, v[188:189]
	v_cvt_pk_bf16_f32 v35, v0, v1
	v_pk_mul_f32 v[0:1], v[2:3], v[34:35] op_sel_hi:[1,0]
	global_store_dword v[32:33], v35, off
